# baseline (speedup 1.0000x reference)
; __device__ __forceinline__ int v_st(int k, int c) { const int kk = (k & ~0xC) | ((k & 4) << 1) | ((k & 8) >> 1); return ((kk >> 3) * 4 + (c >> 5)) * 512 + ((kk & 7) * 32 + (c & 31)) * 2; }
; __device__ __forceinline__ int v_rd_base(int lane) { return ((lane & 3) << 3) | (((lane >> 2) & 3) << 6) | (((lane >> 4) & 1) << 5) | (((lane >> 5) & 1) << 8); }
; #define VMW() asm volatile("s_waitcnt vmcnt(0)" ::: "memory")
; #define SWRITE_HK(bf) do { *(bf16x8*)(lds + AO_K + (bf) * SHM_K + kws) = Sm.st_k0; *(bf16x8*)(lds + AO_K + (bf) * SHM_K + kws + 32 * KPITCH) = Sm.st_k1; \
;         *(bf16x8*)(lds + AO_R + (bf) * SHM_R + rws) = Sm.st_r; } while (0)
; __device__ __forceinline__ void attn_prime(const ABlk& cur, char* lds, ASeam& Sm, const int tid) {
;     const int wid = __builtin_amdgcn_readfirstlane(tid >> 6), lane = tid & 63, r32 = lane & 31, hi = lane >> 5;
;     const int sr = tid >> 4, sc = (tid & 15) * 8, kws = KSWZ(sr, sc * 2), rr = tid >> 3, rc = (tid & 7) * 8, rws = RSWZ(rr, rc * 2);
;     const unsigned kvo = (unsigned)(sr * 128 + sc) * 2u, rvo = (unsigned)(rr * 64 + rc) * 2u;
;     const unsigned qno = (unsigned)((wid * QBLK + r32) * 128 + hi * 8) * 2u, qro = (unsigned)((wid * QBLK + r32) * 64 + hi * 8) * 2u;
; #pragma unroll
;     for (int d0 = 0; d0 < 8; ++d0) Sm.qr[d0] = GL8((const char*)cur.Qn + d0 * 32, qno);
; #pragma unroll
;     for (int d0 = 0; d0 < 4; ++d0) Sm.qr[8 + d0] = GL8((const char*)cur.Qr + d0 * 32, qro);
;     SLOAD_H(cur.Kn, cur.V, cur.Kr, 0); VMW(); SWRITE_HK(0);
;     __syncthreads();
; }
; __device__ __forceinline__ void attn_block(const ABlk& cur, char* lds, ASeam& Sm, const int tid, const int wv) {
;     const int wid = __builtin_amdgcn_readfirstlane(tid >> 6), lane = tid & 63, r32 = lane & 31, hi = lane >> 5;
;     const int NT = cur.P0 / KVBLK + 4;
;     const int qlo = cur.P0 + wid * QBLK, qm = qlo + r32 - 4 * hi;
;     float* wsl = (float*)(lds + AO_W) + wid * 64; float* li_l = wsl; float* al_l = wsl + 32;
;     float m_reg = -1e30f, l_reg = 0; f32x16 o[4] = {};
;     const int sr = tid >> 4, sc = (tid & 15) * 8, vst0 = v_st(sr, sc), vst1 = v_st(32 + sr, sc), kws = KSWZ(sr, sc * 2);
;     const int rr = tid >> 3, rc = (tid & 7) * 8, rws = RSWZ(rr, rc * 2);
;     const unsigned kvo = (unsigned)(sr * 128 + sc) * 2u, rvo = (unsigned)(rr * 64 + rc) * 2u;
;     const int vb0 = (int)(uintptr_t)lds + v_rd_base(lane);
.LBB0_405:
	s_and_b64 s[2:3], s[66:67], exec
	v_readlane_b32 s2, v255, 9
	v_readlane_b32 s3, v255, 10
	s_mov_b64 s[96:97], 0
	s_cselect_b32 s72, s3, s2
	s_add_u32 s2, s88, s96
	s_addc_u32 s3, s89, s97
	s_lshl_b32 s94, s72, 8
	v_readlane_b32 s4, v255, 11
	v_readlane_b32 s5, v255, 12
	s_or_b32 s4, s4, s94
	s_lshl_b64 s[6:7], s[4:5], 8
	s_add_u32 s8, s2, s6
	s_addc_u32 s9, s3, s7
	s_lshl_b64 s[4:5], s[4:5], 7
	s_add_u32 s10, s2, s4
	s_addc_u32 s11, s3, s5
	v_readlane_b32 s4, v255, 15
	v_mov_b32_e32 v0, v1
	v_readlane_b32 s5, v255, 16
	s_add_u32 s6, s2, s4
	s_addc_u32 s7, s3, s5
	v_mbcnt_lo_u32_b32 v0, -1, v0
	s_add_u32 s4, s6, 0x1b980000
	v_mbcnt_hi_u32_b32 v0, -1, v0
	s_addc_u32 s5, s7, 0
	s_waitcnt vmcnt(0)
	v_or_b32_e32 v55, s57, v0
	s_add_u32 s6, s6, 0x1d980000
	s_addc_u32 s7, s7, 0
	v_readfirstlane_b32 s70, v55
	s_ashr_i32 s12, s70, 1
	v_mov_b32_e32 v0, s12
	s_movk_i32 s13, 0xffe0
	v_bfi_b32 v6, s13, v0, v55
	v_lshrrev_b32_e32 v0, 1, v55
	v_and_b32_e32 v7, 16, v0
	v_lshl_or_b32 v0, v6, 8, v7
	v_lshl_add_u64 v[2:3], s[8:9], 0, v[0:1]
	s_mov_b64 s[8:9], 0x18980000
	v_lshl_add_u64 v[4:5], v[2:3], 0, s[8:9]
	s_mov_b32 s8, 0x18980000
	v_add_co_u32_e32 v2, vcc, s8, v2
	v_lshl_or_b32 v0, v6, 7, v7
	s_nop 0
	v_addc_co_u32_e32 v3, vcc, 0, v3, vcc
	global_load_dwordx4 v[138:141], v[4:5], off offset:32
	global_load_dwordx4 v[134:137], v[4:5], off offset:64
	global_load_dwordx4 v[130:133], v[4:5], off offset:96
	global_load_dwordx4 v[126:129], v[4:5], off offset:128
	global_load_dwordx4 v[122:125], v[4:5], off offset:160
	global_load_dwordx4 v[118:121], v[4:5], off offset:192
	global_load_dwordx4 v[142:145], v[2:3], off
	global_load_dwordx4 v[110:113], v[4:5], off offset:224
	v_lshl_add_u64 v[2:3], s[10:11], 0, v[0:1]
	v_lshlrev_b32_e32 v0, 4, v55
	s_mov_b64 s[8:9], 0x1a980000
	v_ashrrev_i32_e32 v22, 3, v55
	v_and_b32_e32 v56, 0x70, v0
	v_ashrrev_i32_e32 v24, 4, v55
	v_lshl_add_u64 v[4:5], v[2:3], 0, s[8:9]
	s_mov_b32 s8, 0x1a980000
	v_lshl_or_b32 v199, v22, 7, v56
	v_and_b32_e32 v23, 0xf0, v0
	v_lshlrev_b32_e32 v25, 8, v24
	v_add_co_u32_e32 v2, vcc, s8, v2
	v_or_b32_e32 v0, v25, v23
	s_waitcnt vmcnt(9)
	v_mov_b32_e32 v10, v199
	v_addc_co_u32_e32 v3, vcc, 0, v3, vcc
	global_load_dwordx4 v[106:109], v[4:5], off offset:32
	global_load_dwordx4 v[102:105], v[4:5], off offset:64
	global_load_dwordx4 v[114:117], v[2:3], off
	global_load_dwordx4 v[98:101], v[4:5], off offset:96
	s_movk_i32 s9, 0x2000
	v_lshl_add_u64 v[6:7], s[4:5], 0, v[0:1]
	v_add_co_u32_e32 v6, vcc, s9, v6
	v_mov_b32_e32 v11, v1
	global_load_dwordx4 v[2:5], v0, s[4:5]
	global_load_dwordx4 v[14:17], v0, s[6:7]
	v_addc_co_u32_e32 v7, vcc, 0, v7, vcc
	v_lshl_add_u64 v[10:11], s[2:3], 0, v[10:11]
	s_mov_b32 s8, 0x18880000
	global_load_dwordx4 v[6:9], v[6:7], off
	v_add_co_u32_e32 v10, vcc, s8, v10
	s_waitcnt vmcnt(15)
	v_lshl_add_u64 v[18:19], s[6:7], 0, v[0:1]
	v_addc_co_u32_e32 v11, vcc, 0, v11, vcc
	global_load_dwordx4 v[10:13], v[10:11], off
	v_add_co_u32_e32 v18, vcc, s9, v18
	v_mul_lo_u32 v0, v24, s14
	s_nop 0
	v_addc_co_u32_e32 v19, vcc, 0, v19, vcc
	global_load_dwordx4 v[18:21], v[18:19], off
	v_add_u32_e32 v58, 0, v0
	v_add_u32_e32 v0, v58, v23
	s_movk_i32 s8, 0x90
	s_waitcnt vmcnt(0)
	v_mul_lo_u32 v59, v22, s8
	v_readlane_b32 s9, v254, 16
	v_and_b32_e32 v54, 31, v55
	s_and_b32 s95, s12, 0xffffffe0
	s_add_i32 s33, s95, s94
	s_waitcnt vmcnt(4)
	ds_write_b128 v0, v[2:5] offset:32768
	s_waitcnt vmcnt(2)
	ds_write_b128 v0, v[6:9] offset:41472
	v_and_b32_e32 v3, 0xfffff0, v24
	v_lshlrev_b32_e32 v4, 1, v24
	v_bfe_u32 v8, v55, 5, 1
	v_and_or_b32 v3, v4, 8, v3
	v_lshrrev_b32_e32 v4, 1, v24
	v_and_b32_e32 v5, 3, v24
	v_add3_u32 v0, s9, v59, v56
	v_lshlrev_b32_e32 v57, 2, v8
	v_and_or_b32 v4, v4, 4, v5
	v_add_u32_e32 v5, 32, v24
	s_waitcnt vmcnt(1)
	ds_write_b128 v0, v[10:13]
	v_sub_u32_e32 v0, v54, v57
	v_and_b32_e32 v6, 0xfffff0, v5
	v_lshlrev_b32_e32 v5, 1, v5
	v_add_u32_e32 v197, s33, v0
	v_lshlrev_b32_e32 v0, 3, v55
	v_and_or_b32 v5, v5, 8, v6
	v_and_b32_e32 v2, 0x78, v0
	v_lshrrev_b32_e32 v3, 1, v3
	v_bfe_u32 v0, v0, 5, 2
	v_lshrrev_b32_e32 v5, 1, v5
	v_or_b32_e32 v3, v3, v0
	v_lshlrev_b32_e32 v61, 1, v2
	v_or_b32_e32 v0, v5, v0
	v_lshlrev_b32_e32 v3, 9, v3
	v_lshlrev_b32_e32 v4, 6, v4
	v_and_b32_e32 v2, 48, v61
	v_lshlrev_b32_e32 v0, 9, v0
	v_or3_b32 v3, v3, v4, v2
	v_or3_b32 v0, v0, v4, v2
	v_or_b32_e32 v201, v61, v25
	v_add_u32_e32 v202, 0, v3
	v_add_u32_e32 v203, 0, v0
	s_waitcnt lgkmcnt(0)
	s_barrier
; #define SBAR() __builtin_amdgcn_sched_barrier(0)
; #define SWRITE_HV(bf) do { *(bf16x8*)(lds + AO_V + (bf) * SHM_V + vst0) = Sm.st_v0; *(bf16x8*)(lds + AO_V + (bf) * SHM_V + vst1) = Sm.st_v1; } while (0)
; template <int KB>
; __device__ __forceinline__ void qkt(f32x16& p0, f32x16& p1, const char* lds, int r32, int hi, const bf16x8* qr) {
;     p0 = f32x16{}; p1 = f32x16{};
;     const char* kb = lds + AO_K + KB * SHM_K + KSWZ(r32, hi * 16); const char* rb = lds + AO_R + KB * SHM_R + RSWZ(r32, hi * 16);
; #pragma unroll
;     for (int d0 = 0; d0 < 8; ++d0) { const char* a = kb + d0 * 32;
;         bf16x8 b0 = *reinterpret_cast<const bf16x8*>(a);
;         bf16x8 b1 = *reinterpret_cast<const bf16x8*>(a + 32 * KPITCH);
;         p0 = __builtin_amdgcn_mfma_f32_32x32x16_bf16(b0, qr[d0], p0, 0, 0, 0);
;         p1 = __builtin_amdgcn_mfma_f32_32x32x16_bf16(b1, qr[d0], p1, 0, 0, 0); }
; #pragma unroll
;     for (int d0 = 0; d0 < 4; ++d0) { const char* a = rb + d0 * 32;
;         bf16x8 b0 = *reinterpret_cast<const bf16x8*>(a);
;         bf16x8 b1 = *reinterpret_cast<const bf16x8*>(a + 32 * RPITCH);
;         p0 = __builtin_amdgcn_mfma_f32_32x32x16_bf16(b0, qr[8 + d0], p0, 0, 0, 0);
;         p1 = __builtin_amdgcn_mfma_f32_32x32x16_bf16(b1, qr[8 + d0], p1, 0, 0, 0); }
; }
; __device__ __forceinline__ void attn_block(const ABlk& cur, char* lds, ASeam& Sm, const int tid, const int wv) {
;     ...
;     SWRITE_HV(0); SBAR();
;     SLOAD_H(Kh, Vh, Rh, KBASE(1));
;     SBAR(); qkt<0>(pA0, pA1, lds, r32, hi, Sm.qr);
	ds_write_b128 v202, v[14:17]
	s_waitcnt vmcnt(0)
	ds_write_b128 v203, v[18:21]
	v_mov_b32_e32 v2, v199
	v_mov_b32_e32 v0, v201
	v_mov_b32_e32 v3, v1
	v_lshl_add_u64 v[4:5], s[6:7], 0, v[0:1]
	s_movk_i32 s6, 0x4000
	v_add_co_u32_e32 v6, vcc, s6, v4
	s_movk_i32 s7, 0x6000
	s_nop 0
	v_addc_co_u32_e32 v7, vcc, 0, v5, vcc
	v_add_co_u32_e32 v4, vcc, s7, v4
	v_lshl_add_u64 v[2:3], s[2:3], 0, v[2:3]
	s_nop 0
	v_addc_co_u32_e32 v5, vcc, 0, v5, vcc
	global_load_dwordx4 v[34:37], v[6:7], off
	global_load_dwordx4 v[38:41], v[4:5], off
	v_lshl_add_u64 v[4:5], s[4:5], 0, v[0:1]
	v_add_co_u32_e32 v6, vcc, s6, v4
	s_mov_b32 s4, 0x18882000
	s_nop 0
	v_addc_co_u32_e32 v7, vcc, 0, v5, vcc
	v_add_co_u32_e32 v4, vcc, s7, v4
	s_nop 1
	v_addc_co_u32_e32 v5, vcc, 0, v5, vcc
	v_add_co_u32_e32 v2, vcc, s4, v2
	global_load_dwordx4 v[42:45], v[6:7], off
	global_load_dwordx4 v[46:49], v[4:5], off
	v_addc_co_u32_e32 v3, vcc, 0, v3, vcc
	global_load_dwordx4 v[50:53], v[2:3], off
	v_lshlrev_b32_e32 v60, 4, v8
	v_mad_u32_u24 v0, v54, s14, 0
	v_add_u32_e32 v200, v0, v60
	ds_read_b128 v[66:69], v200 offset:32768
	ds_read_b128 v[70:73], v200 offset:41472
	ds_read_b128 v[74:77], v200 offset:32800
	ds_read_b128 v[78:81], v200 offset:41504
	v_mov_b32_e32 v0, s9
	v_mad_u32_u24 v0, v54, s8, v0
	v_add_u32_e32 v204, v0, v60
	s_cmp_gt_i32 s33, 62
	ds_read_b128 v[82:85], v200 offset:32832
	ds_read_b128 v[86:89], v200 offset:41536
	s_waitcnt lgkmcnt(4)
	v_mfma_f32_32x32x16_bf16 v[2:17], v[66:69], v[142:145], 0
	v_mfma_f32_32x32x16_bf16 v[18:33], v[70:73], v[142:145], 0
	ds_read_b128 v[66:69], v200 offset:32864
	ds_read_b128 v[70:73], v200 offset:41568
	s_waitcnt lgkmcnt(2)
	v_mfma_f32_32x32x16_bf16 v[2:17], v[74:77], v[138:141], v[2:17]
	v_mfma_f32_32x32x16_bf16 v[18:33], v[78:81], v[138:141], v[18:33]
	ds_read_b128 v[74:77], v200 offset:32896
	ds_read_b128 v[78:81], v200 offset:41600
	s_waitcnt lgkmcnt(2)
	v_mfma_f32_32x32x16_bf16 v[2:17], v[82:85], v[134:137], v[2:17]
	v_mfma_f32_32x32x16_bf16 v[18:33], v[86:89], v[134:137], v[18:33]
	ds_read_b128 v[82:85], v200 offset:32928
	ds_read_b128 v[86:89], v200 offset:41632
	s_waitcnt lgkmcnt(2)
	v_mfma_f32_32x32x16_bf16 v[2:17], v[66:69], v[130:133], v[2:17]
	v_mfma_f32_32x32x16_bf16 v[18:33], v[70:73], v[130:133], v[18:33]
	ds_read_b128 v[66:69], v200 offset:32960
	ds_read_b128 v[70:73], v200 offset:41664
	s_waitcnt lgkmcnt(2)
	v_mfma_f32_32x32x16_bf16 v[2:17], v[74:77], v[126:129], v[2:17]
	v_mfma_f32_32x32x16_bf16 v[18:33], v[78:81], v[126:129], v[18:33]
	ds_read_b128 v[74:77], v200 offset:32992
	ds_read_b128 v[78:81], v200 offset:41696
	s_waitcnt lgkmcnt(2)
	v_mfma_f32_32x32x16_bf16 v[2:17], v[82:85], v[122:125], v[2:17]
	v_mfma_f32_32x32x16_bf16 v[18:33], v[86:89], v[122:125], v[18:33]
	ds_read_b128 v[82:85], v204
	ds_read_b128 v[86:89], v204 offset:4608
	s_waitcnt lgkmcnt(2)
	v_mfma_f32_32x32x16_bf16 v[2:17], v[66:69], v[118:121], v[2:17]
	v_mfma_f32_32x32x16_bf16 v[18:33], v[70:73], v[118:121], v[18:33]
	ds_read_b128 v[66:69], v204 offset:32
	ds_read_b128 v[70:73], v204 offset:4640
	s_waitcnt lgkmcnt(2)
	v_mfma_f32_32x32x16_bf16 v[2:17], v[74:77], v[110:113], v[2:17]
	v_mfma_f32_32x32x16_bf16 v[18:33], v[78:81], v[110:113], v[18:33]
	ds_read_b128 v[74:77], v204 offset:64
	ds_read_b128 v[78:81], v204 offset:4672
	s_waitcnt lgkmcnt(2)
	v_mfma_f32_32x32x16_bf16 v[2:17], v[82:85], v[114:117], v[2:17]
	v_mfma_f32_32x32x16_bf16 v[18:33], v[86:89], v[114:117], v[18:33]
	ds_read_b128 v[82:85], v204 offset:96
	ds_read_b128 v[86:89], v204 offset:4704
	s_waitcnt lgkmcnt(2)
	v_mfma_f32_32x32x16_bf16 v[2:17], v[66:69], v[106:109], v[2:17]
	v_mfma_f32_32x32x16_bf16 v[18:33], v[70:73], v[106:109], v[18:33]
	s_waitcnt lgkmcnt(2)
	v_mfma_f32_32x32x16_bf16 v[2:17], v[74:77], v[102:105], v[2:17]
	v_mfma_f32_32x32x16_bf16 v[18:33], v[78:81], v[102:105], v[18:33]
	s_waitcnt lgkmcnt(0)
	v_mfma_f32_32x32x16_bf16 v[2:17], v[82:85], v[98:101], v[2:17]
	v_mfma_f32_32x32x16_bf16 v[18:33], v[86:89], v[98:101], v[18:33]
	s_cbranch_scc1 .LBB0_407
; __device__ __forceinline__ void mask_tile(f32x16& p0, f32x16& p1, int dq) {
;     const float NEG = -__builtin_inff();
; #pragma unroll
;     for (int r = 0; r < 16; ++r) { const int c = (r & 3) + 8 * (r >> 2);
;         if (dq - c < 0) p0[r] = NEG;
;         if (dq - c - 32 < 0) p1[r] = NEG; }
; }
	v_cmp_gt_i32_e64 s[62:63], 26, v197
	v_cmp_gt_i32_e64 s[64:65], 27, v197
	v_cmp_gt_i32_e64 s[60:61], 25, v197
	s_and_b64 s[62:63], s[64:65], s[62:63]
	v_cmp_gt_i32_e64 s[58:59], 24, v197
	s_and_b64 s[60:61], s[62:63], s[60:61]
	v_cmp_gt_i32_e64 s[56:57], 19, v197
	s_and_b64 s[58:59], s[60:61], s[58:59]
	v_cmp_gt_i32_e64 s[54:55], 18, v197
	s_and_b64 s[56:57], s[58:59], s[56:57]
	v_cmp_gt_i32_e64 s[52:53], 17, v197
	s_and_b64 s[54:55], s[56:57], s[54:55]
	v_cmp_gt_i32_e64 s[50:51], 16, v197
	s_and_b64 s[52:53], s[54:55], s[52:53]
	v_cmp_gt_i32_e64 s[48:49], 11, v197
	s_and_b64 s[50:51], s[52:53], s[50:51]
	v_cmp_gt_i32_e64 s[46:47], 10, v197
	s_and_b64 s[48:49], s[50:51], s[48:49]
	v_cmp_gt_i32_e64 s[44:45], 9, v197
	s_and_b64 s[46:47], s[48:49], s[46:47]
	v_cmp_gt_i32_e64 s[42:43], 8, v197
	s_and_b64 s[44:45], s[46:47], s[44:45]
	v_cmp_gt_i32_e64 s[40:41], 3, v197
	s_and_b64 s[42:43], s[44:45], s[42:43]
	v_cmp_gt_i32_e64 s[38:39], 2, v197
	s_and_b64 s[40:41], s[42:43], s[40:41]
	v_cmp_gt_i32_e64 s[36:37], 1, v197
	s_and_b64 s[38:39], s[40:41], s[38:39]
	v_cmp_gt_i32_e64 s[34:35], 0, v197
	s_and_b64 s[36:37], s[38:39], s[36:37]
	s_and_b64 s[34:35], s[36:37], s[34:35]
	v_cmp_gt_i32_e64 s[30:31], 58, v197
	v_cndmask_b32_e64 v2, v2, v186, s[34:35]
	v_cmp_gt_i32_e64 s[34:35], 59, v197
	v_cmp_gt_i32_e64 s[28:29], 57, v197
	s_and_b64 s[30:31], s[34:35], s[30:31]
	v_cmp_gt_i32_e64 s[26:27], 56, v197
	s_and_b64 s[28:29], s[30:31], s[28:29]
	v_cmp_gt_i32_e64 s[24:25], 51, v197
	s_and_b64 s[26:27], s[28:29], s[26:27]
	v_cmp_gt_i32_e64 s[22:23], 50, v197
	s_and_b64 s[24:25], s[26:27], s[24:25]
	v_cmp_gt_i32_e64 s[20:21], 49, v197
	s_and_b64 s[22:23], s[24:25], s[22:23]
	v_cmp_gt_i32_e64 s[18:19], 48, v197
	s_and_b64 s[20:21], s[22:23], s[20:21]
	v_cmp_gt_i32_e64 s[16:17], 43, v197
	s_and_b64 s[18:19], s[20:21], s[18:19]
	v_cmp_gt_i32_e64 s[14:15], 42, v197
	s_and_b64 s[16:17], s[18:19], s[16:17]
	v_cmp_gt_i32_e64 s[12:13], 41, v197
	s_and_b64 s[14:15], s[16:17], s[14:15]
	v_cmp_gt_i32_e64 s[10:11], 40, v197
	s_and_b64 s[12:13], s[14:15], s[12:13]
	v_cmp_gt_i32_e64 s[8:9], 35, v197
	s_and_b64 s[10:11], s[12:13], s[10:11]
	v_cmp_gt_i32_e64 s[6:7], 34, v197
	s_and_b64 s[8:9], s[10:11], s[8:9]
	v_cmp_gt_i32_e64 s[4:5], 33, v197
	s_and_b64 s[6:7], s[8:9], s[6:7]
	v_cmp_gt_i32_e32 vcc, 32, v197
	s_and_b64 s[4:5], s[6:7], s[4:5]
	s_and_b64 vcc, s[4:5], vcc
	v_cndmask_b32_e64 v17, v17, v186, s[64:65]
	v_cndmask_b32_e64 v16, v16, v186, s[62:63]
	v_cndmask_b32_e64 v15, v15, v186, s[60:61]
	v_cndmask_b32_e64 v14, v14, v186, s[58:59]
	v_cndmask_b32_e64 v13, v13, v186, s[56:57]
	v_cndmask_b32_e64 v12, v12, v186, s[54:55]
	v_cndmask_b32_e64 v11, v11, v186, s[52:53]
	v_cndmask_b32_e64 v10, v10, v186, s[50:51]
	v_cndmask_b32_e64 v9, v9, v186, s[48:49]
	v_cndmask_b32_e64 v8, v8, v186, s[46:47]
	v_cndmask_b32_e64 v7, v7, v186, s[44:45]
	v_cndmask_b32_e64 v6, v6, v186, s[42:43]
	v_cndmask_b32_e64 v5, v5, v186, s[40:41]
	v_cndmask_b32_e64 v4, v4, v186, s[38:39]
	v_cndmask_b32_e64 v3, v3, v186, s[36:37]
	v_cndmask_b32_e64 v33, v33, v186, s[34:35]
	v_cndmask_b32_e64 v32, v32, v186, s[30:31]
	v_cndmask_b32_e64 v31, v31, v186, s[28:29]
	v_cndmask_b32_e64 v30, v30, v186, s[26:27]
	v_cndmask_b32_e64 v29, v29, v186, s[24:25]
	v_cndmask_b32_e64 v28, v28, v186, s[22:23]
	v_cndmask_b32_e64 v27, v27, v186, s[20:21]
	v_cndmask_b32_e64 v26, v26, v186, s[18:19]
	v_cndmask_b32_e64 v25, v25, v186, s[16:17]
	v_cndmask_b32_e64 v24, v24, v186, s[14:15]
	v_cndmask_b32_e64 v23, v23, v186, s[12:13]
	v_cndmask_b32_e64 v22, v22, v186, s[10:11]
	v_cndmask_b32_e64 v21, v21, v186, s[8:9]
	v_cndmask_b32_e64 v20, v20, v186, s[6:7]
	v_cndmask_b32_e64 v19, v19, v186, s[4:5]
	v_cndmask_b32_e32 v18, v18, v186, vcc

; __device__ __forceinline__ void finishSM(f32x16& p0, f32x16& p1, float alpha, float& l_reg, bf16x8& pa0, bf16x8& pa1, bf16x8& pa2, bf16x8& pa3) {
; #pragma unroll
;     for (int r = 0; r < 16; ++r) p1[r] = __builtin_amdgcn_exp2f(p1[r]);
;     float ps = 0;
; #pragma unroll
;     for (int r = 0; r < 16; ++r) ps += p0[r];
; #pragma unroll
;     for (int r = 0; r < 16; ++r) ps += p1[r];
;     { auto rr = __builtin_amdgcn_permlane32_swap(__float_as_uint(ps), __float_as_uint(ps), false, false);
;       ps = __uint_as_float(rr[0]) + __uint_as_float(rr[1]); }
;     l_reg = l_reg * alpha + ps;
;     ...
;     PK4(p0, 0, pa0); PK4(p0, 8, pa1); PK4(p1, 0, pa2); PK4(p1, 8, pa3);
;     ...
; }
; template <int KB>
; __device__ __forceinline__ void qkt(f32x16& p0, f32x16& p1, const char* lds, int r32, int hi, const bf16x8* qr) {
;     p0 = f32x16{}; p1 = f32x16{};
;     const char* kb = lds + AO_K + KB * SHM_K + KSWZ(r32, hi * 16); const char* rb = lds + AO_R + KB * SHM_R + RSWZ(r32, hi * 16);
; #pragma unroll
;     for (int d0 = 0; d0 < 8; ++d0) { const char* a = kb + d0 * 32;
;         bf16x8 b0 = *reinterpret_cast<const bf16x8*>(a);
;         bf16x8 b1 = *reinterpret_cast<const bf16x8*>(a + 32 * KPITCH);
;         p0 = __builtin_amdgcn_mfma_f32_32x32x16_bf16(b0, qr[d0], p0, 0, 0, 0);
;         p1 = __builtin_amdgcn_mfma_f32_32x32x16_bf16(b1, qr[d0], p1, 0, 0, 0); }
; #pragma unroll
;     for (int d0 = 0; d0 < 4; ++d0) { const char* a = rb + d0 * 32;
;         bf16x8 b0 = *reinterpret_cast<const bf16x8*>(a);
;         bf16x8 b1 = *reinterpret_cast<const bf16x8*>(a + 32 * RPITCH);
;         p0 = __builtin_amdgcn_mfma_f32_32x32x16_bf16(b0, qr[8 + d0], p0, 0, 0, 0);
;         p1 = __builtin_amdgcn_mfma_f32_32x32x16_bf16(b1, qr[8 + d0], p1, 0, 0, 0); }
; }
.LBB0_426:
	v_exp_f32_e32 v166, v166
	v_exp_f32_e32 v175, v175
	v_exp_f32_e32 v167, v167
	v_exp_f32_e32 v176, v176
	v_exp_f32_e32 v168, v168
	v_exp_f32_e32 v177, v177
	v_exp_f32_e32 v169, v169
	v_exp_f32_e32 v174, v174
	v_exp_f32_e32 v165, v165
	v_exp_f32_e32 v170, v170
	v_exp_f32_e32 v171, v171
	v_exp_f32_e32 v172, v172
	v_exp_f32_e32 v162, v162
	v_exp_f32_e32 v164, v164
	v_exp_f32_e32 v163, v163
	v_exp_f32_e32 v173, v173
	ds_read_b128 v[220:223], v200 offset:50176
	ds_read_b128 v[224:227], v200 offset:58880
	ds_read_b128 v[228:231], v200 offset:50208
	ds_read_b128 v[232:235], v200 offset:58912
	ds_read_b128 v[242:245], v200 offset:50240
	ds_read_b128 v[246:249], v200 offset:58944
	s_waitcnt lgkmcnt(4)
	v_mfma_f32_32x32x16_bf16 v[82:97], v[220:223], v[142:145], 0
	v_mfma_f32_32x32x16_bf16 v[66:81], v[224:227], v[142:145], 0
	ds_read_b128 v[220:223], v200 offset:50272
	ds_read_b128 v[224:227], v200 offset:58976
	s_waitcnt lgkmcnt(2)
	v_mfma_f32_32x32x16_bf16 v[82:97], v[228:231], v[138:141], v[82:97]
	v_mfma_f32_32x32x16_bf16 v[66:81], v[232:235], v[138:141], v[66:81]
	ds_read_b128 v[228:231], v200 offset:50304
	ds_read_b128 v[232:235], v200 offset:59008
	s_waitcnt lgkmcnt(2)
	v_mfma_f32_32x32x16_bf16 v[82:97], v[242:245], v[134:137], v[82:97]
	v_mfma_f32_32x32x16_bf16 v[66:81], v[246:249], v[134:137], v[66:81]
	ds_read_b128 v[242:245], v200 offset:50336
	ds_read_b128 v[246:249], v200 offset:59040
	s_waitcnt lgkmcnt(2)
	v_mfma_f32_32x32x16_bf16 v[82:97], v[220:223], v[130:133], v[82:97]
	v_mfma_f32_32x32x16_bf16 v[66:81], v[224:227], v[130:133], v[66:81]
	ds_read_b128 v[220:223], v200 offset:50368
	ds_read_b128 v[224:227], v200 offset:59072
	s_waitcnt lgkmcnt(2)
	v_mfma_f32_32x32x16_bf16 v[82:97], v[228:231], v[126:129], v[82:97]
	v_mfma_f32_32x32x16_bf16 v[66:81], v[232:235], v[126:129], v[66:81]
	ds_read_b128 v[228:231], v200 offset:50400
	ds_read_b128 v[232:235], v200 offset:59104
	s_waitcnt lgkmcnt(2)
	v_mfma_f32_32x32x16_bf16 v[82:97], v[242:245], v[122:125], v[82:97]
	v_mfma_f32_32x32x16_bf16 v[66:81], v[246:249], v[122:125], v[66:81]
	ds_read_b128 v[242:245], v205
	ds_read_b128 v[246:249], v205 offset:4608
	s_waitcnt lgkmcnt(2)
	v_mfma_f32_32x32x16_bf16 v[82:97], v[220:223], v[118:121], v[82:97]
	v_mfma_f32_32x32x16_bf16 v[66:81], v[224:227], v[118:121], v[66:81]
	ds_read_b128 v[220:223], v205 offset:32
	ds_read_b128 v[224:227], v205 offset:4640
	s_waitcnt lgkmcnt(2)
	v_mfma_f32_32x32x16_bf16 v[82:97], v[228:231], v[110:113], v[82:97]
	v_mfma_f32_32x32x16_bf16 v[66:81], v[232:235], v[110:113], v[66:81]
	ds_read_b128 v[228:231], v205 offset:64
	ds_read_b128 v[232:235], v205 offset:4672
	s_waitcnt lgkmcnt(2)
	v_mfma_f32_32x32x16_bf16 v[82:97], v[242:245], v[114:117], v[82:97]
	v_mfma_f32_32x32x16_bf16 v[66:81], v[246:249], v[114:117], v[66:81]
	ds_read_b128 v[242:245], v205 offset:96
	ds_read_b128 v[246:249], v205 offset:4704
	s_waitcnt lgkmcnt(2)
	v_mfma_f32_32x32x16_bf16 v[82:97], v[220:223], v[106:109], v[82:97]
	v_mfma_f32_32x32x16_bf16 v[66:81], v[224:227], v[106:109], v[66:81]
	s_waitcnt lgkmcnt(2)
	v_mfma_f32_32x32x16_bf16 v[82:97], v[228:231], v[102:105], v[82:97]
	v_mfma_f32_32x32x16_bf16 v[66:81], v[232:235], v[102:105], v[66:81]
	s_waitcnt lgkmcnt(0)
	v_mfma_f32_32x32x16_bf16 v[82:97], v[242:245], v[98:101], v[82:97]
	v_mfma_f32_32x32x16_bf16 v[66:81], v[246:249], v[98:101], v[66:81]
	v_add_f32_e32 v98, 0, v166
	v_add_f32_e32 v98, v175, v98
	v_add_f32_e32 v98, v167, v98
	v_add_f32_e32 v98, v176, v98
	v_add_f32_e32 v98, v168, v98
	v_add_f32_e32 v98, v177, v98
	v_add_f32_e32 v98, v169, v98
	v_add_f32_e32 v98, v174, v98
	v_add_f32_e32 v98, v165, v98
	v_add_f32_e32 v98, v170, v98
	v_add_f32_e32 v98, v171, v98
	v_add_f32_e32 v98, v172, v98
	v_exp_f32_e32 v108, v160
	v_add_f32_e32 v98, v162, v98
	v_exp_f32_e32 v109, v161
	v_add_f32_e32 v98, v164, v98
	v_exp_f32_e32 v110, v158
	v_add_f32_e32 v98, v163, v98
	v_exp_f32_e32 v111, v159
	v_add_f32_e32 v98, v173, v98
	v_exp_f32_e32 v112, v154
	v_add_f32_e32 v98, v108, v98
	v_exp_f32_e32 v113, v155
	v_add_f32_e32 v98, v109, v98
	v_exp_f32_e32 v114, v150
	v_add_f32_e32 v98, v110, v98
	v_exp_f32_e32 v115, v151
	v_add_f32_e32 v98, v111, v98
	v_exp_f32_e32 v116, v146
	v_add_f32_e32 v98, v112, v98
	v_exp_f32_e32 v117, v147
	v_add_f32_e32 v98, v113, v98
	v_exp_f32_e32 v118, v156
	v_add_f32_e32 v98, v114, v98
	v_exp_f32_e32 v119, v157
	v_add_f32_e32 v98, v115, v98
	v_exp_f32_e32 v120, v152
	v_add_f32_e32 v98, v116, v98
	v_exp_f32_e32 v121, v153
	v_add_f32_e32 v98, v117, v98
	v_exp_f32_e32 v122, v148
	v_add_f32_e32 v98, v118, v98
	v_exp_f32_e32 v123, v149
	v_add_f32_e32 v98, v119, v98
	v_add_f32_e32 v98, v120, v98
	v_add_f32_e32 v98, v121, v98
	v_add_f32_e32 v98, v122, v98
	v_add_f32_e32 v98, v123, v98
	v_mov_b32_e32 v99, v98
	s_nop 1
	v_permlane32_swap_b32_e32 v98, v99
	v_cvt_pk_bf16_f32 v100, v166, v175
	v_cvt_pk_bf16_f32 v101, v167, v176
	v_cvt_pk_bf16_f32 v102, v168, v177
	v_cvt_pk_bf16_f32 v103, v169, v174
	v_cvt_pk_bf16_f32 v104, v165, v170
	v_cvt_pk_bf16_f32 v105, v171, v172
	v_cvt_pk_bf16_f32 v106, v162, v164
	v_cvt_pk_bf16_f32 v107, v163, v173
	v_cvt_pk_bf16_f32 v108, v108, v109
	v_cvt_pk_bf16_f32 v109, v110, v111
	v_cvt_pk_bf16_f32 v110, v112, v113
	v_cvt_pk_bf16_f32 v111, v114, v115
	v_cvt_pk_bf16_f32 v112, v116, v117
	v_cvt_pk_bf16_f32 v113, v118, v119
	v_cvt_pk_bf16_f32 v114, v120, v121
	v_cvt_pk_bf16_f32 v115, v122, v123
	s_nop 0
	v_permlane32_swap_b32_e32 v100, v102
	v_permlane32_swap_b32_e32 v101, v103
	v_permlane32_swap_b32_e32 v104, v106
	v_permlane32_swap_b32_e32 v105, v107
	v_permlane32_swap_b32_e32 v108, v110
	v_permlane32_swap_b32_e32 v109, v111
	v_permlane32_swap_b32_e32 v112, v114
	v_permlane32_swap_b32_e32 v113, v115
	ds_read_b64_tr_b16 v[116:117], v194 offset:0
	ds_read_b64_tr_b16 v[118:119], v194 offset:0x800
	ds_read_b64_tr_b16 v[120:121], v194 offset:0x1000
	ds_read_b64_tr_b16 v[122:123], v194 offset:0x1800
	ds_read_b64_tr_b16 v[124:125], v194 offset:0x2000
	ds_read_b64_tr_b16 v[126:127], v194 offset:0x2800
	ds_read_b64_tr_b16 v[128:129], v194 offset:0x3000
	ds_read_b64_tr_b16 v[130:131], v194 offset:0x3800
	s_waitcnt lgkmcnt(0)
; __device__ __forceinline__ void mask_tile(f32x16& p0, f32x16& p1, int dq) {
;     const float NEG = -__builtin_inff();
; #pragma unroll
;     for (int r = 0; r < 16; ++r) { const int c = (r & 3) + 8 * (r >> 2);
;         if (dq - c < 0) p0[r] = NEG;
;         if (dq - c - 32 < 0) p1[r] = NEG; }
; }
; template <int VB>
; __device__ __forceinline__ void pv_tile(f32x16* o, int vb0, bf16x8 pa0, bf16x8 pa1, bf16x8 pa2, bf16x8 pa3) {
;     ...
;     PV_D0(0); PV_D0(1); PV_D0(2); PV_D0(3);
	s_nop 0
	v_mfma_f32_32x32x16_bf16 v[50:65], v[100:103], v[116:119], v[50:65]
	ds_read_b64_tr_b16 v[116:117], v194 offset:0x200
	ds_read_b64_tr_b16 v[118:119], v194 offset:0xa00
	v_mfma_f32_32x32x16_bf16 v[50:65], v[104:107], v[120:123], v[50:65]
	ds_read_b64_tr_b16 v[120:121], v194 offset:0x1200
	ds_read_b64_tr_b16 v[122:123], v194 offset:0x1a00
	v_mfma_f32_32x32x16_bf16 v[50:65], v[108:111], v[124:127], v[50:65]
	ds_read_b64_tr_b16 v[124:125], v194 offset:0x2200
	ds_read_b64_tr_b16 v[126:127], v194 offset:0x2a00
	v_mfma_f32_32x32x16_bf16 v[50:65], v[112:115], v[128:131], v[50:65]
	ds_read_b64_tr_b16 v[128:129], v194 offset:0x3200
	ds_read_b64_tr_b16 v[130:131], v194 offset:0x3a00
	s_waitcnt lgkmcnt(0)
	v_mfma_f32_32x32x16_bf16 v[34:49], v[100:103], v[116:119], v[34:49]
	ds_read_b64_tr_b16 v[116:117], v194 offset:0x400
	ds_read_b64_tr_b16 v[118:119], v194 offset:0xc00
	v_mfma_f32_32x32x16_bf16 v[34:49], v[104:107], v[120:123], v[34:49]
	ds_read_b64_tr_b16 v[120:121], v194 offset:0x1400
	ds_read_b64_tr_b16 v[122:123], v194 offset:0x1c00
	v_mfma_f32_32x32x16_bf16 v[34:49], v[108:111], v[124:127], v[34:49]
	ds_read_b64_tr_b16 v[124:125], v194 offset:0x2400
	ds_read_b64_tr_b16 v[126:127], v194 offset:0x2c00
	v_mfma_f32_32x32x16_bf16 v[34:49], v[112:115], v[128:131], v[34:49]
	ds_read_b64_tr_b16 v[128:129], v194 offset:0x3400
	ds_read_b64_tr_b16 v[130:131], v194 offset:0x3c00
	s_waitcnt lgkmcnt(0)
	v_mfma_f32_32x32x16_bf16 v[18:33], v[100:103], v[116:119], v[18:33]
	ds_read_b64_tr_b16 v[116:117], v194 offset:0x600
	ds_read_b64_tr_b16 v[118:119], v194 offset:0xe00
	v_mfma_f32_32x32x16_bf16 v[18:33], v[104:107], v[120:123], v[18:33]
	ds_read_b64_tr_b16 v[120:121], v194 offset:0x1600
	ds_read_b64_tr_b16 v[122:123], v194 offset:0x1e00
	v_mfma_f32_32x32x16_bf16 v[18:33], v[108:111], v[124:127], v[18:33]
	ds_read_b64_tr_b16 v[124:125], v194 offset:0x2600
	ds_read_b64_tr_b16 v[126:127], v194 offset:0x2e00
	v_mfma_f32_32x32x16_bf16 v[18:33], v[112:115], v[128:131], v[18:33]
	ds_read_b64_tr_b16 v[128:129], v194 offset:0x3600
	ds_read_b64_tr_b16 v[130:131], v194 offset:0x3e00
	s_waitcnt lgkmcnt(0)
	v_mfma_f32_32x32x16_bf16 v[2:17], v[100:103], v[116:119], v[2:17]
	s_cmpk_lt_i32 s95, 0xff
	v_mfma_f32_32x32x16_bf16 v[2:17], v[104:107], v[120:123], v[2:17]
	v_mfma_f32_32x32x16_bf16 v[2:17], v[108:111], v[124:127], v[2:17]
	v_mfma_f32_32x32x16_bf16 v[2:17], v[112:115], v[128:131], v[2:17]
	s_cbranch_scc0 .LBB0_428
	v_subrev_u32_e32 v100, s94, v197
	v_add_u32_e32 v100, 0xffffff40, v100
	v_cmp_gt_i32_e64 s[64:65], 26, v100
	v_cmp_gt_i32_e64 s[66:67], 27, v100
	v_cmp_gt_i32_e64 s[62:63], 25, v100
	s_and_b64 s[64:65], s[66:67], s[64:65]
	v_cmp_gt_i32_e64 s[60:61], 24, v100
	s_and_b64 s[62:63], s[64:65], s[62:63]
	v_cmp_gt_i32_e64 s[58:59], 19, v100
	s_and_b64 s[60:61], s[62:63], s[60:61]
	v_cmp_gt_i32_e64 s[56:57], 18, v100
	s_and_b64 s[58:59], s[60:61], s[58:59]
	v_cmp_gt_i32_e64 s[54:55], 17, v100
	s_and_b64 s[56:57], s[58:59], s[56:57]
	v_cmp_gt_i32_e64 s[52:53], 16, v100
	s_and_b64 s[54:55], s[56:57], s[54:55]
	v_cmp_gt_i32_e64 s[50:51], 11, v100
	s_and_b64 s[52:53], s[54:55], s[52:53]
	v_cmp_gt_i32_e64 s[48:49], 10, v100
	s_and_b64 s[50:51], s[52:53], s[50:51]
	v_cmp_gt_i32_e64 s[46:47], 9, v100
	s_and_b64 s[48:49], s[50:51], s[48:49]
	v_cmp_gt_i32_e64 s[44:45], 8, v100
	s_and_b64 s[46:47], s[48:49], s[46:47]
	v_cmp_gt_i32_e64 s[42:43], 3, v100
	s_and_b64 s[44:45], s[46:47], s[44:45]
	v_cmp_gt_i32_e64 s[40:41], 2, v100
	s_and_b64 s[42:43], s[44:45], s[42:43]
	v_cmp_gt_i32_e64 s[38:39], 1, v100
	s_and_b64 s[40:41], s[42:43], s[40:41]
	v_cmp_gt_i32_e64 s[36:37], 0, v100
	s_and_b64 s[38:39], s[40:41], s[38:39]
	s_and_b64 s[36:37], s[38:39], s[36:37]
	v_cmp_gt_i32_e64 s[34:35], 58, v100
	v_cndmask_b32_e64 v82, v82, v186, s[36:37]
	v_cmp_gt_i32_e64 s[36:37], 59, v100
	v_cmp_gt_i32_e64 s[30:31], 57, v100
	s_and_b64 s[34:35], s[36:37], s[34:35]
	v_cmp_gt_i32_e64 s[28:29], 56, v100
	s_and_b64 s[30:31], s[34:35], s[30:31]
	v_cmp_gt_i32_e64 s[26:27], 51, v100
	s_and_b64 s[28:29], s[30:31], s[28:29]
	v_cmp_gt_i32_e64 s[24:25], 50, v100
	s_and_b64 s[26:27], s[28:29], s[26:27]
	v_cmp_gt_i32_e64 s[22:23], 49, v100
	s_and_b64 s[24:25], s[26:27], s[24:25]
	v_cmp_gt_i32_e64 s[20:21], 48, v100
	s_and_b64 s[22:23], s[24:25], s[22:23]
	v_cmp_gt_i32_e64 s[18:19], 43, v100
	s_and_b64 s[20:21], s[22:23], s[20:21]
	v_cmp_gt_i32_e64 s[16:17], 42, v100
	s_and_b64 s[18:19], s[20:21], s[18:19]
	v_cmp_gt_i32_e64 s[14:15], 41, v100
	s_and_b64 s[16:17], s[18:19], s[16:17]
	v_cmp_gt_i32_e64 s[12:13], 40, v100
	s_and_b64 s[14:15], s[16:17], s[14:15]
	v_cmp_gt_i32_e64 s[10:11], 35, v100
	s_and_b64 s[12:13], s[14:15], s[12:13]
	v_cmp_gt_i32_e64 s[8:9], 34, v100
	s_and_b64 s[10:11], s[12:13], s[10:11]
	v_cmp_gt_i32_e64 s[6:7], 33, v100
	s_and_b64 s[8:9], s[10:11], s[8:9]
	v_cmp_gt_i32_e32 vcc, 32, v100
	s_and_b64 s[6:7], s[8:9], s[6:7]
	s_and_b64 vcc, s[6:7], vcc
	v_cndmask_b32_e64 v97, v97, v186, s[66:67]
	v_cndmask_b32_e64 v96, v96, v186, s[64:65]
	v_cndmask_b32_e64 v95, v95, v186, s[62:63]
	v_cndmask_b32_e64 v94, v94, v186, s[60:61]
	v_cndmask_b32_e64 v93, v93, v186, s[58:59]
	v_cndmask_b32_e64 v92, v92, v186, s[56:57]
	v_cndmask_b32_e64 v91, v91, v186, s[54:55]
	v_cndmask_b32_e64 v90, v90, v186, s[52:53]
	v_cndmask_b32_e64 v89, v89, v186, s[50:51]
	v_cndmask_b32_e64 v88, v88, v186, s[48:49]
	v_cndmask_b32_e64 v87, v87, v186, s[46:47]
	v_cndmask_b32_e64 v86, v86, v186, s[44:45]
	v_cndmask_b32_e64 v85, v85, v186, s[42:43]
	v_cndmask_b32_e64 v84, v84, v186, s[40:41]
	v_cndmask_b32_e64 v83, v83, v186, s[38:39]
	v_cndmask_b32_e64 v81, v81, v186, s[36:37]
	v_cndmask_b32_e64 v80, v80, v186, s[34:35]
	v_cndmask_b32_e64 v79, v79, v186, s[30:31]
	v_cndmask_b32_e64 v78, v78, v186, s[28:29]
	v_cndmask_b32_e64 v77, v77, v186, s[26:27]
	v_cndmask_b32_e64 v76, v76, v186, s[24:25]
	v_cndmask_b32_e64 v75, v75, v186, s[22:23]
	v_cndmask_b32_e64 v74, v74, v186, s[20:21]
	v_cndmask_b32_e64 v73, v73, v186, s[18:19]
	v_cndmask_b32_e64 v72, v72, v186, s[16:17]
	v_cndmask_b32_e64 v71, v71, v186, s[14:15]
	v_cndmask_b32_e64 v70, v70, v186, s[12:13]
	v_cndmask_b32_e64 v69, v69, v186, s[10:11]
	v_cndmask_b32_e64 v68, v68, v186, s[8:9]
	v_cndmask_b32_e64 v67, v67, v186, s[6:7]
	v_cndmask_b32_e32 v66, v66, v186, vcc
